# GEMM tile head trimmed: gsz==8 division by shift/and, scalar swap flag, scalar has-next test (wave-uniform branch tests shortened) + conv barrier decision via SCC branches
# baseline (speedup 1.0000x reference)
;   __device__ bool next(int i, Unit& u) const {
;     const long L = (long)i * G + c; if (L >= nwg) return false;
;     int wgid = (int)L; { const int q = nwg / NXCD, r = nwg % NXCD, xcd = wgid % NXCD, off = wgid / NXCD; wgid = (xcd < r ? xcd * (q + 1) : r * (q + 1) + (xcd - r) * q) + off; }
;     const int nig = WGM * nN, gid = wgid / nig, fm = gid * WGM, gsz = (nM - fm) < WGM ? (nM - fm) : WGM;
;     u.pm = fm + ((wgid % nig) % gsz); u.pn = (wgid % nig) / gsz; u.swap = (u.pn >= slo && u.pn < shi) ? 1 : 0; return true;
; template <class Epi>
; __device__ __forceinline__ void gemm_phase(LAS unsigned char* lds, const Gemm g, const StaticOrder& S, const Epi& E) {
;     ...
;     const bool has_next = S.next(ui + 1, nxt);
;     const char* nA = cA; const char* nB = cB;
;     if (has_next) { const char* qa = (const char*)g.A + (size_t)nxt.pm * tstep; const char* qb = (const char*)g.Bt + (size_t)nxt.pn * tstep; nA = nxt.swap ? qb : qa; nB = nxt.swap ? qa : qb; }
.LBB0_51:
	s_add_i32 s68, s68, 1
	v_readlane_b32 s0, v253, 15
	v_readlane_b32 s8, v253, 6
	s_mul_i32 s0, s68, s0
	s_mul_hi_u32 s1, s68, s8
	s_add_i32 s1, s1, s0
	s_mul_i32 s0, s68, s8
	v_readlane_b32 s8, v253, 9
	s_mov_b64 s[12:13], s[16:17]
	s_add_u32 s16, s0, s8
	v_readlane_b32 s0, v253, 13
	s_addc_u32 s17, s1, s0
	s_mov_b64 s[10:11], s[18:19]
	s_mov_b32 s73, s87
	s_mov_b32 s72, s86
	s_mov_b32 s71, s24
	s_cmp_ge_u32 s16, s92
	s_cselect_b64 s[8:9], -1, 0
	s_cselect_b64 s[0:1], 0, -1
	s_cbranch_scc1 .LBB0_53
	s_ashr_i32 s17, s16, 31
	s_lshr_b32 s17, s17, 29
	s_add_i32 s17, s16, s17
	s_ashr_i32 s18, s17, 3
	s_and_b32 s17, s17, -8
	s_sub_i32 s16, s16, s17
	s_lshr_b32 s17, s16, 31
	s_or_b32 s17, s81, s17
	s_mul_i32 s16, s17, s16
	s_add_i32 s16, s16, s18
	s_abs_i32 s18, s16
	s_mul_hi_u32 s19, s18, s70
	s_mul_i32 s24, s19, s3
	s_ashr_i32 s17, s16, 31
	s_sub_i32 s18, s18, s24
	s_xor_b32 s17, s17, s69
	s_add_i32 s24, s19, 1
	s_sub_i32 s74, s18, s3
	s_cmp_ge_u32 s18, s3
	s_cselect_b32 s19, s24, s19
	s_cselect_b32 s18, s74, s18
	s_add_i32 s24, s19, 1
	s_cmp_ge_u32 s18, s3
	s_cselect_b32 s18, s24, s19
	s_xor_b32 s18, s18, s17
	s_sub_i32 s17, s18, s17
	s_lshl_b32 s18, s17, 3
	s_mul_i32 s17, s17, s80
	s_sub_i32 s16, s16, s17
	s_lshr_b32 s86, s16, 3
	s_and_b32 s16, s16, 7
	s_add_i32 s87, s16, s18
	v_readlane_b32 s16, v254, 37
	v_readlane_b32 s18, v254, 35
	s_cmp_ge_i32 s86, s16
	s_cselect_b32 s16, 1, 0
	s_cmp_lt_i32 s86, s18
	s_cselect_b32 s18, 1, 0
	s_and_b32 s24, s16, s18
